# scan chain: LDS reads hoisted 8 slots ahead with renamed registers (on top of wkv resident params, prefetch de-serialization, P6 gate batching)
# speedup vs baseline: 1.0748x; 1.0026x over previous
.LBB0_1023:
	s_bitcmp1_b32 s76, 0
	s_cselect_b32 s77, 0x11400, 0
	s_add_i32 s77, s77, 0
	v_add_u32_e32 v136, s77, v96
	v_add_u32_e32 v137, v136, v76
	v_add_u32_e32 v138, s77, v98
	ds_read2st64_b64 v[140:143], v137 offset0:18 offset1:41
	ds_read_b128 v[148:151], v138 offset:11520
	v_add_u32_e32 v139, s77, v76
	v_add_u32_e32 v152, v139, v96
	ds_read2_b64 v[156:159], v152 offset1:4
	ds_read2_b64 v[160:163], v152 offset0:8 offset1:12
	v_add_u32_e32 v153, v136, v92
	ds_read2st64_b64 v[168:171], v153 offset0:18 offset1:41
	v_add_u32_e32 v154, s77, v91
	ds_read_b128 v[176:179], v154 offset:11520
	v_add_u32_e32 v155, 0x800, v152
	ds_read2_b64 v[180:183], v155 offset0:32 offset1:36
	v_add_u32_e32 v165, v136, v90
	ds_read2_b64 v[184:187], v155 offset0:40 offset1:44
	v_add_u32_e32 v155, s77, v89
	ds_read2st64_b64 v[188:191], v165 offset0:18 offset1:41
	ds_read_b128 v[192:195], v155 offset:11520
	v_cvt_pk_bf16_f32 v52, v40, v41
	v_cvt_pk_bf16_f32 v53, v42, v43
	s_waitcnt lgkmcnt(9)
	v_lshlrev_b32_e32 v64, 16, v140
	v_and_b32_e32 v65, 0xffff0000, v140
	v_lshlrev_b32_e32 v70, 16, v141
	v_and_b32_e32 v71, 0xffff0000, v141
	s_waitcnt lgkmcnt(8)
	v_pk_fma_f32 v[42:43], v[42:43], v[150:151], v[70:71]
	v_pk_fma_f32 v[40:41], v[40:41], v[148:149], v[64:65]
	v_add_u32_e32 v148, 0x1000, v152
	ds_read2_b64 v[196:199], v148 offset0:64 offset1:68
	v_cvt_pk_bf16_f32 v54, v36, v37
	v_cvt_pk_bf16_f32 v55, v38, v39
	v_cvt_pk_bf16_f32 v56, v44, v45
	v_cvt_pk_bf16_f32 v57, v46, v47
	s_waitcnt lgkmcnt(8)
	v_mfma_f32_16x16x32_bf16 v[40:43], v[156:159], v[52:55], v[40:43]
	v_add_u32_e32 v149, v136, v88
	ds_read2_b64 v[156:159], v148 offset0:72 offset1:76
	v_cvt_pk_bf16_f32 v58, v48, v49
	v_cvt_pk_bf16_f32 v59, v50, v51
	v_add_u32_e32 v136, s77, v86
	ds_read2st64_b64 v[200:203], v149 offset0:18 offset1:41
	s_waitcnt lgkmcnt(9)
	v_mfma_f32_16x16x32_bf16 v[40:43], v[160:163], v[56:59], v[40:43]
	ds_read_b128 v[160:163], v136 offset:11520
	s_waitcnt lgkmcnt(9)
	v_lshlrev_b32_e32 v60, 16, v168
	v_and_b32_e32 v61, 0xffff0000, v168
	v_lshlrev_b32_e32 v70, 16, v169
	v_and_b32_e32 v71, 0xffff0000, v169
	s_waitcnt lgkmcnt(8)
	v_pk_fma_f32 v[36:37], v[36:37], v[176:177], v[60:61]
	v_pk_fma_f32 v[38:39], v[38:39], v[178:179], v[70:71]
	v_add_u32_e32 v148, v139, v87
	ds_read2_b64 v[176:179], v148 offset1:4
	s_waitcnt lgkmcnt(8)
	v_mfma_f32_16x16x32_bf16 v[36:39], v[180:183], v[52:55], v[36:39]
	ds_read2_b64 v[180:183], v148 offset0:8 offset1:12
	ds_read_b128 v[204:207], v138 offset:23296
	s_waitcnt lgkmcnt(9)
	v_mfma_f32_16x16x32_bf16 v[36:39], v[184:187], v[56:59], v[36:39]
	v_add_u32_e32 v139, 0x2800, v152
	ds_read2_b64 v[184:187], v139 offset0:192 offset1:196
	s_waitcnt lgkmcnt(9)
	v_lshlrev_b32_e32 v70, 16, v188
	v_and_b32_e32 v71, 0xffff0000, v188
	v_lshlrev_b32_e32 v114, 16, v189
	v_and_b32_e32 v115, 0xffff0000, v189
	s_waitcnt lgkmcnt(8)
	v_pk_fma_f32 v[46:47], v[46:47], v[194:195], v[114:115]
	v_pk_fma_f32 v[44:45], v[44:45], v[192:193], v[70:71]
	ds_read2_b64 v[192:195], v139 offset0:200 offset1:204
	s_waitcnt lgkmcnt(8)
	v_mfma_f32_16x16x32_bf16 v[44:47], v[196:199], v[52:55], v[44:47]
	ds_read_b128 v[196:199], v154 offset:23296
	v_add_u32_e32 v139, 0xb800, v152
	v_add_u32_e32 v150, 0x3000, v152
	ds_read2_b64 v[208:211], v150 offset0:224 offset1:228
	s_waitcnt lgkmcnt(9)
	v_mfma_f32_16x16x32_bf16 v[44:47], v[156:159], v[56:59], v[44:47]
	ds_read2_b64 v[156:159], v150 offset0:232 offset1:236
	s_waitcnt lgkmcnt(9)
	v_lshlrev_b32_e32 v70, 16, v200
	v_and_b32_e32 v71, 0xffff0000, v200
	v_lshlrev_b32_e32 v114, 16, v201
	v_and_b32_e32 v115, 0xffff0000, v201
	s_waitcnt lgkmcnt(8)
	v_pk_fma_f32 v[50:51], v[50:51], v[162:163], v[114:115]
	v_pk_fma_f32 v[48:49], v[48:49], v[160:161], v[70:71]
	ds_read_b128 v[160:163], v155 offset:23296
	v_lshl_add_u64 v[66:67], v[82:83], 0, s[24:25]
	global_store_dwordx2 v[66:67], v[52:53], off nt
	global_store_dwordx2 v[66:67], v[54:55], off offset:32 nt
	s_waitcnt lgkmcnt(8)
	v_mfma_f32_16x16x32_bf16 v[48:51], v[176:179], v[52:55], v[48:51]
	v_add_u32_e32 v150, 0x4000, v152
	ds_read2_b64 v[176:179], v150 offset1:4
	ds_read2_b64 v[212:215], v150 offset0:8 offset1:12
	v_add_co_u32_e32 v70, vcc, s10, v66
	s_waitcnt lgkmcnt(9)
	v_mfma_f32_16x16x32_bf16 v[48:51], v[180:183], v[56:59], v[48:51]
	global_store_dwordx2 v[66:67], v[56:57], off offset:64 nt
	global_store_dwordx2 v[66:67], v[58:59], off offset:96 nt
	v_cvt_pk_bf16_f32 v52, v40, v41
	v_cvt_pk_bf16_f32 v53, v42, v43
	v_addc_co_u32_e32 v71, vcc, 0, v67, vcc
	v_cvt_pk_bf16_f32 v54, v36, v37
	v_cvt_pk_bf16_f32 v55, v38, v39
	v_cvt_pk_bf16_f32 v56, v44, v45
	v_cvt_pk_bf16_f32 v57, v46, v47
	v_cvt_pk_bf16_f32 v58, v48, v49
	v_cvt_pk_bf16_f32 v59, v50, v51
	global_store_dwordx2 v[70:71], v[52:53], off nt
	global_store_dwordx2 v[70:71], v[54:55], off offset:32 nt
	global_store_dwordx2 v[70:71], v[56:57], off offset:64 nt
	global_store_dwordx2 v[70:71], v[58:59], off offset:96 nt
	v_lshlrev_b32_e32 v70, 16, v142
	v_and_b32_e32 v71, 0xffff0000, v142
	v_lshlrev_b32_e32 v108, 16, v143
	v_and_b32_e32 v109, 0xffff0000, v143
	s_waitcnt lgkmcnt(8)
	v_pk_fma_f32 v[40:41], v[40:41], v[204:205], v[70:71]
	v_pk_fma_f32 v[42:43], v[42:43], v[206:207], v[108:109]
	ds_read_b128 v[140:143], v136 offset:23296
	v_and_b32_e32 v71, 0xffff0000, v170
	s_waitcnt lgkmcnt(8)
	v_mfma_f32_16x16x32_bf16 v[40:43], v[184:187], v[52:55], v[40:43]
	v_add_u32_e32 v150, 0x2800, v148
	ds_read2_b64 v[180:183], v150 offset0:192 offset1:196
	v_lshlrev_b32_e32 v70, 16, v170
	v_lshlrev_b32_e32 v112, 16, v171
	s_waitcnt lgkmcnt(8)
	v_mfma_f32_16x16x32_bf16 v[40:43], v[192:195], v[56:59], v[40:43]
	ds_read2_b64 v[184:187], v150 offset0:200 offset1:204
	v_and_b32_e32 v113, 0xffff0000, v171
	s_mov_b32 s78, 0x8000
	s_waitcnt lgkmcnt(8)
	v_pk_fma_f32 v[36:37], v[36:37], v[196:197], v[70:71]
	v_pk_fma_f32 v[38:39], v[38:39], v[198:199], v[112:113]
	ds_read_b128 v[168:171], v138 offset:35072
	v_and_b32_e32 v71, 0xffff0000, v190
	s_waitcnt lgkmcnt(8)
	v_mfma_f32_16x16x32_bf16 v[36:39], v[208:211], v[52:55], v[36:39]
	ds_read2st64_b64 v[192:195], v137 offset0:64 offset1:87
	v_lshlrev_b32_e32 v70, 16, v190
	v_lshlrev_b32_e32 v112, 16, v191
	s_waitcnt lgkmcnt(8)
	v_mfma_f32_16x16x32_bf16 v[36:39], v[156:159], v[56:59], v[36:39]
	v_add_u32_e32 v150, 0x5800, v152
	ds_read2_b64 v[156:159], v150 offset0:128 offset1:132
	v_and_b32_e32 v113, 0xffff0000, v191
	s_waitcnt lgkmcnt(8)
	v_pk_fma_f32 v[44:45], v[44:45], v[160:161], v[70:71]
	v_pk_fma_f32 v[46:47], v[46:47], v[162:163], v[112:113]
	ds_read2_b64 v[160:163], v150 offset0:136 offset1:140
	v_and_b32_e32 v71, 0xffff0000, v202
	s_waitcnt lgkmcnt(8)
	v_mfma_f32_16x16x32_bf16 v[44:47], v[176:179], v[52:55], v[44:47]
	ds_read_b128 v[176:179], v154 offset:35072
	v_lshlrev_b32_e32 v70, 16, v202
	v_lshlrev_b32_e32 v112, 16, v203
	s_waitcnt lgkmcnt(8)
	v_mfma_f32_16x16x32_bf16 v[44:47], v[212:215], v[56:59], v[44:47]
	ds_read2st64_b64 v[188:191], v153 offset0:64 offset1:87
	v_and_b32_e32 v113, 0xffff0000, v203
	s_waitcnt lgkmcnt(8)
	v_pk_fma_f32 v[48:49], v[48:49], v[140:141], v[70:71]
	v_pk_fma_f32 v[50:51], v[50:51], v[142:143], v[112:113]
	v_add_u32_e32 v140, 0x6000, v152
	ds_read2_b64 v[196:199], v140 offset0:160 offset1:164
	s_waitcnt lgkmcnt(8)
	v_mfma_f32_16x16x32_bf16 v[48:51], v[180:183], v[52:55], v[48:51]
	ds_read2_b64 v[180:183], v140 offset0:168 offset1:172
	v_add_co_u32_e32 v70, vcc, s11, v66
	s_waitcnt lgkmcnt(8)
	v_mfma_f32_16x16x32_bf16 v[48:51], v[184:187], v[56:59], v[48:51]
	v_cvt_pk_bf16_f32 v52, v40, v41
	v_cvt_pk_bf16_f32 v53, v42, v43
	v_addc_co_u32_e32 v71, vcc, 0, v67, vcc
	v_cvt_pk_bf16_f32 v54, v36, v37
	v_cvt_pk_bf16_f32 v55, v38, v39
	v_cvt_pk_bf16_f32 v56, v44, v45
	v_cvt_pk_bf16_f32 v57, v46, v47
	s_nop 0
	v_cvt_pk_bf16_f32 v58, v48, v49
	v_cvt_pk_bf16_f32 v59, v50, v51
	global_store_dwordx2 v[70:71], v[52:53], off nt
	global_store_dwordx2 v[70:71], v[54:55], off offset:32 nt
	global_store_dwordx2 v[70:71], v[56:57], off offset:64 nt
	global_store_dwordx2 v[70:71], v[58:59], off offset:96 nt
	ds_read_b128 v[140:143], v155 offset:35072
	ds_read2st64_b64 v[184:187], v165 offset0:64 offset1:87
	s_waitcnt lgkmcnt(8)
	v_lshlrev_b32_e32 v70, 16, v192
	v_and_b32_e32 v71, 0xffff0000, v192
	v_lshlrev_b32_e32 v112, 16, v193
	v_and_b32_e32 v113, 0xffff0000, v193
	v_pk_fma_f32 v[40:41], v[40:41], v[168:169], v[70:71]
	v_pk_fma_f32 v[42:43], v[42:43], v[170:171], v[112:113]
	v_add_u32_e32 v150, 0x6800, v152
	ds_read2_b64 v[168:171], v150 offset0:192 offset1:196
	s_waitcnt lgkmcnt(8)
	v_mfma_f32_16x16x32_bf16 v[40:43], v[156:159], v[52:55], v[40:43]
	ds_read2_b64 v[156:159], v150 offset0:200 offset1:204
	s_waitcnt lgkmcnt(8)
	v_mfma_f32_16x16x32_bf16 v[40:43], v[160:163], v[56:59], v[40:43]
	ds_read_b128 v[160:163], v136 offset:35072
	ds_read2st64_b64 v[200:203], v149 offset0:64 offset1:87
	s_nop 5
	v_cvt_pk_bf16_f32 v128, v40, v41
	v_cvt_pk_bf16_f32 v129, v42, v43
	s_waitcnt lgkmcnt(8)
	v_lshlrev_b32_e32 v70, 16, v188
	v_and_b32_e32 v71, 0xffff0000, v188
	v_lshlrev_b32_e32 v112, 16, v189
	v_and_b32_e32 v113, 0xffff0000, v189
	v_pk_fma_f32 v[36:37], v[36:37], v[176:177], v[70:71]
	v_pk_fma_f32 v[38:39], v[38:39], v[178:179], v[112:113]
	v_add_u32_e32 v150, 0x5800, v148
	ds_read2_b64 v[176:179], v150 offset0:128 offset1:132
	s_waitcnt lgkmcnt(8)
	v_mfma_f32_16x16x32_bf16 v[36:39], v[196:199], v[52:55], v[36:39]
	ds_read2_b64 v[196:199], v150 offset0:136 offset1:140
	s_waitcnt lgkmcnt(8)
	v_mfma_f32_16x16x32_bf16 v[36:39], v[180:183], v[56:59], v[36:39]
	ds_read_b128 v[180:183], v138 offset:46848
	v_add_u32_e32 v150, 0x8800, v152
	ds_read2_b64 v[204:207], v150 offset0:64 offset1:68
	s_nop 5
	v_cvt_pk_bf16_f32 v130, v36, v37
	v_cvt_pk_bf16_f32 v131, v38, v39
	s_waitcnt lgkmcnt(8)
	v_lshlrev_b32_e32 v70, 16, v184
	v_and_b32_e32 v71, 0xffff0000, v184
	v_lshlrev_b32_e32 v112, 16, v185
	v_and_b32_e32 v113, 0xffff0000, v185
	v_pk_fma_f32 v[44:45], v[44:45], v[140:141], v[70:71]
	v_pk_fma_f32 v[46:47], v[46:47], v[142:143], v[112:113]
	ds_read2_b64 v[140:143], v150 offset0:72 offset1:76
	s_waitcnt lgkmcnt(8)
	v_mfma_f32_16x16x32_bf16 v[44:47], v[168:171], v[52:55], v[44:47]
	ds_read_b128 v[168:171], v154 offset:46848
	s_waitcnt lgkmcnt(8)
	v_mfma_f32_16x16x32_bf16 v[44:47], v[156:159], v[56:59], v[44:47]
	v_add_u32_e32 v150, 0x9000, v152
	ds_read2_b64 v[156:159], v150 offset0:96 offset1:100
	ds_read2_b64 v[208:211], v150 offset0:104 offset1:108
	s_nop 5
	v_cvt_pk_bf16_f32 v132, v44, v45
	v_cvt_pk_bf16_f32 v133, v46, v47
	s_waitcnt lgkmcnt(8)
	v_lshlrev_b32_e32 v70, 16, v200
	v_and_b32_e32 v71, 0xffff0000, v200
	v_lshlrev_b32_e32 v112, 16, v201
	v_and_b32_e32 v113, 0xffff0000, v201
	v_pk_fma_f32 v[48:49], v[48:49], v[160:161], v[70:71]
	v_pk_fma_f32 v[50:51], v[50:51], v[162:163], v[112:113]
	ds_read_b128 v[160:163], v155 offset:46848
	s_waitcnt lgkmcnt(8)
	v_mfma_f32_16x16x32_bf16 v[48:51], v[176:179], v[52:55], v[48:51]
	v_add_u32_e32 v150, 0x9800, v152
	ds_read2_b64 v[176:179], v150 offset0:128 offset1:132
	s_waitcnt lgkmcnt(8)
	v_mfma_f32_16x16x32_bf16 v[108:111], v[196:199], v[56:59], v[48:51]
	s_nop 4
	v_add_co_u32_e32 v48, vcc, s33, v66
	v_lshlrev_b32_e32 v52, 16, v194
	s_nop 0
	v_addc_co_u32_e32 v49, vcc, 0, v67, vcc
	v_cvt_pk_bf16_f32 v134, v108, v109
	v_cvt_pk_bf16_f32 v135, v110, v111
	global_store_dwordx2 v[48:49], v[128:129], off nt
	global_store_dwordx2 v[48:49], v[130:131], off offset:32 nt
	global_store_dwordx2 v[48:49], v[132:133], off offset:64 nt
	global_store_dwordx2 v[48:49], v[134:135], off offset:96 nt
	ds_read2_b64 v[196:199], v150 offset0:136 offset1:140
	v_and_b32_e32 v53, 0xffff0000, v194
	v_lshlrev_b32_e32 v54, 16, v195
	v_and_b32_e32 v55, 0xffff0000, v195
	v_add_co_u32_e32 v70, vcc, s78, v66
	s_waitcnt lgkmcnt(8)
	v_pk_fma_f32 v[40:41], v[40:41], v[180:181], v[52:53]
	v_pk_fma_f32 v[42:43], v[42:43], v[182:183], v[54:55]
	v_add_u32_e32 v150, 0x8800, v148
	ds_read_b128 v[180:183], v136 offset:46848
	v_and_b32_e32 v53, 0xffff0000, v190
	s_waitcnt lgkmcnt(8)
	v_mfma_f32_16x16x32_bf16 v[40:43], v[204:207], v[128:131], v[40:43]
	ds_read2_b64 v[192:195], v150 offset0:64 offset1:68
	v_lshlrev_b32_e32 v52, 16, v190
	v_lshlrev_b32_e32 v54, 16, v191
	s_waitcnt lgkmcnt(8)
	v_mfma_f32_16x16x32_bf16 v[48:51], v[140:143], v[132:135], v[40:43]
	s_nop 2
	ds_read2_b64 v[140:143], v150 offset0:72 offset1:76
	v_and_b32_e32 v55, 0xffff0000, v191
	v_addc_co_u32_e32 v71, vcc, 0, v67, vcc
	s_add_i32 s78, s77, 0x11300
	s_waitcnt lgkmcnt(8)
	v_pk_fma_f32 v[36:37], v[36:37], v[168:169], v[52:53]
	v_pk_fma_f32 v[38:39], v[38:39], v[170:171], v[54:55]
	ds_read_b128 v[168:171], v138 offset:58624
	s_add_i32 s77, s77, 0x10a00
	s_waitcnt lgkmcnt(8)
	v_mfma_f32_16x16x32_bf16 v[36:39], v[156:159], v[128:131], v[36:39]
	ds_read_b64 v[150:151], v137 offset:56320
	s_waitcnt lgkmcnt(8)
	v_mfma_f32_16x16x32_bf16 v[56:59], v[208:211], v[132:135], v[36:39]
	s_nop 4
	ds_read2_b64 v[156:159], v139 offset1:4
	v_lshlrev_b32_e32 v40, 16, v186
	v_and_b32_e32 v41, 0xffff0000, v186
	v_lshlrev_b32_e32 v42, 16, v187
	v_and_b32_e32 v43, 0xffff0000, v187
	s_waitcnt lgkmcnt(8)
	v_pk_fma_f32 v[36:37], v[44:45], v[160:161], v[40:41]
	v_pk_fma_f32 v[38:39], v[46:47], v[162:163], v[42:43]
	ds_read2_b64 v[160:163], v139 offset0:8 offset1:12
	s_waitcnt lgkmcnt(8)
	v_mfma_f32_16x16x32_bf16 v[36:39], v[176:179], v[128:131], v[36:39]
	v_add_u32_e32 v137, s77, v96
	ds_read_b128 v[176:179], v154 offset:58624
	s_waitcnt lgkmcnt(8)
	v_mfma_f32_16x16x32_bf16 v[52:55], v[196:199], v[132:135], v[36:39]
	s_nop 3
	ds_read_b64 v[138:139], v153 offset:56320
	v_lshlrev_b32_e32 v40, 16, v202
	v_and_b32_e32 v41, 0xffff0000, v202
	v_lshlrev_b32_e32 v42, 16, v203
	v_and_b32_e32 v43, 0xffff0000, v203
	s_waitcnt lgkmcnt(8)
	v_pk_fma_f32 v[38:39], v[110:111], v[182:183], v[42:43]
	v_pk_fma_f32 v[36:37], v[108:109], v[180:181], v[40:41]
	v_add_u32_e32 v153, 0xc000, v152
	ds_read2_b64 v[180:183], v153 offset0:32 offset1:36
	s_waitcnt lgkmcnt(8)
	v_mfma_f32_16x16x32_bf16 v[36:39], v[192:195], v[128:131], v[36:39]
	ds_read2_b64 v[184:187], v153 offset0:40 offset1:44
	s_waitcnt lgkmcnt(8)
	v_mfma_f32_16x16x32_bf16 v[44:47], v[140:143], v[132:135], v[36:39]
	v_cvt_pk_bf16_f32 v40, v48, v49
	v_cvt_pk_bf16_f32 v41, v50, v51
	v_cvt_pk_bf16_f32 v42, v56, v57
	v_cvt_pk_bf16_f32 v43, v58, v59
	s_nop 0
	v_cvt_pk_bf16_f32 v36, v52, v53
	v_cvt_pk_bf16_f32 v37, v54, v55
	s_nop 0
	v_cvt_pk_bf16_f32 v38, v44, v45
	v_cvt_pk_bf16_f32 v39, v46, v47
	global_store_dwordx2 v[70:71], v[40:41], off nt
	global_store_dwordx2 v[70:71], v[42:43], off offset:32 nt
	global_store_dwordx2 v[70:71], v[36:37], off offset:64 nt
	global_store_dwordx2 v[70:71], v[38:39], off offset:96 nt
	ds_read_b128 v[140:143], v155 offset:58624
	ds_read_b64 v[154:155], v165 offset:56320
	s_waitcnt lgkmcnt(8)
	v_lshlrev_b32_e32 v70, 16, v150
	v_and_b32_e32 v71, 0xffff0000, v150
	v_lshlrev_b32_e32 v68, 16, v151
	v_and_b32_e32 v69, 0xffff0000, v151
	v_pk_fma_f32 v[50:51], v[50:51], v[170:171], v[68:69]
	v_pk_fma_f32 v[48:49], v[48:49], v[168:169], v[70:71]
	v_add_u32_e32 v150, 0xc800, v152
	ds_read2_b64 v[168:171], v150 offset0:64 offset1:68
	s_waitcnt lgkmcnt(8)
	v_mfma_f32_16x16x32_bf16 v[48:51], v[156:159], v[40:43], v[48:51]
	ds_read2_b64 v[156:159], v150 offset0:72 offset1:76
	s_waitcnt lgkmcnt(8)
	v_mfma_f32_16x16x32_bf16 v[48:51], v[160:163], v[36:39], v[48:51]
	ds_read_b128 v[160:163], v136 offset:58624
	ds_read_b64 v[150:151], v149 offset:56320
	s_waitcnt lgkmcnt(8)
	v_lshlrev_b32_e32 v110, 16, v138
	v_and_b32_e32 v111, 0xffff0000, v138
	v_lshlrev_b32_e32 v108, 16, v139
	v_and_b32_e32 v109, 0xffff0000, v139
	v_pk_fma_f32 v[58:59], v[58:59], v[178:179], v[108:109]
	v_pk_fma_f32 v[56:57], v[56:57], v[176:177], v[110:111]
	v_add_u32_e32 v136, 0xb800, v148
	ds_read2_b64 v[176:179], v136 offset1:4
	s_waitcnt lgkmcnt(8)
	v_mfma_f32_16x16x32_bf16 v[56:59], v[180:183], v[40:43], v[56:59]
	ds_read2_b64 v[180:183], v136 offset0:8 offset1:12
	s_waitcnt lgkmcnt(8)
	v_mfma_f32_16x16x32_bf16 v[56:59], v[184:187], v[36:39], v[56:59]
	v_add_u32_e32 v136, s78, v98
	v_add_u32_e32 v138, v137, v76
	ds_read_b128 v[184:187], v136
	ds_read_b64 v[166:167], v138
	s_waitcnt lgkmcnt(8)
	v_lshlrev_b32_e32 v108, 16, v154
	v_and_b32_e32 v109, 0xffff0000, v154
	v_lshlrev_b32_e32 v62, 16, v155
	v_and_b32_e32 v63, 0xffff0000, v155
	v_pk_fma_f32 v[54:55], v[54:55], v[142:143], v[62:63]
	v_pk_fma_f32 v[52:53], v[52:53], v[140:141], v[108:109]
	v_add_u32_e32 v136, 0xe000, v152
	ds_read2_b64 v[140:143], v136 offset0:192 offset1:196
	s_waitcnt lgkmcnt(8)
	v_mfma_f32_16x16x32_bf16 v[52:55], v[168:171], v[40:43], v[52:55]
	v_add_u32_e32 v138, 0xe800, v152
	ds_read2_b64 v[168:171], v136 offset0:200 offset1:204
	v_add_u32_e32 v136, v137, v92
	ds_read_b64 v[154:155], v136
	v_add_u32_e32 v136, s78, v91
	ds_read_b128 v[188:191], v136
	s_waitcnt lgkmcnt(10)
	v_mfma_f32_16x16x32_bf16 v[52:55], v[156:159], v[36:39], v[52:55]
	s_waitcnt lgkmcnt(8)
	v_lshlrev_b32_e32 v68, 16, v150
	v_and_b32_e32 v69, 0xffff0000, v150
	v_lshlrev_b32_e32 v64, 16, v151
	v_and_b32_e32 v65, 0xffff0000, v151
	v_pk_fma_f32 v[46:47], v[46:47], v[162:163], v[64:65]
	v_pk_fma_f32 v[44:45], v[44:45], v[160:161], v[68:69]
	ds_read2_b64 v[156:159], v138 offset0:224 offset1:228
	v_cvt_pk_bf16_f32 v65, v50, v51
	s_waitcnt lgkmcnt(8)
	v_mfma_f32_16x16x32_bf16 v[40:43], v[176:179], v[40:43], v[44:47]
	s_nop 2
	v_add_u32_e32 v136, 0xe000, v148
	ds_read2_b64 v[148:151], v138 offset0:232 offset1:236
	v_cvt_pk_bf16_f32 v64, v48, v49
	v_cvt_pk_bf16_f32 v60, v52, v53
	s_waitcnt lgkmcnt(8)
	v_mfma_f32_16x16x32_bf16 v[68:71], v[180:183], v[36:39], v[40:43]
	v_add_co_u32_e32 v36, vcc, s34, v66
	v_cvt_pk_bf16_f32 v66, v56, v57
	s_nop 0
	v_addc_co_u32_e32 v37, vcc, 0, v67, vcc
	v_cvt_pk_bf16_f32 v67, v58, v59
	v_cvt_pk_bf16_f32 v61, v54, v55
	s_nop 1
	v_cvt_pk_bf16_f32 v62, v68, v69
	v_cvt_pk_bf16_f32 v63, v70, v71
	global_store_dwordx2 v[36:37], v[64:65], off nt
	global_store_dwordx2 v[36:37], v[66:67], off offset:32 nt
	global_store_dwordx2 v[36:37], v[60:61], off offset:64 nt
	global_store_dwordx2 v[36:37], v[62:63], off offset:96 nt
	v_add_u32_e32 v138, v137, v90
	ds_read_b64 v[160:161], v138
	v_add_u32_e32 v138, s78, v89
	ds_read_b128 v[176:179], v138
	s_waitcnt lgkmcnt(8)
	v_lshlrev_b32_e32 v42, 16, v166
	v_and_b32_e32 v43, 0xffff0000, v166
	v_lshlrev_b32_e32 v40, 16, v167
	v_and_b32_e32 v41, 0xffff0000, v167
	v_pk_fma_f32 v[38:39], v[50:51], v[186:187], v[40:41]
	v_pk_fma_f32 v[36:37], v[48:49], v[184:185], v[42:43]
	v_add_u32_e32 v138, 0xf800, v152
	ds_read2_b64 v[180:183], v138 offset1:4
	s_waitcnt lgkmcnt(8)
	v_mfma_f32_16x16x32_bf16 v[36:39], v[140:143], v[64:67], v[36:39]
	ds_read2_b64 v[140:143], v138 offset0:8 offset1:12
	v_add_u32_e32 v138, v137, v88
	ds_read_b64 v[152:153], v138
	s_waitcnt lgkmcnt(9)
	v_mfma_f32_16x16x32_bf16 v[40:43], v[168:171], v[60:63], v[36:39]
	s_nop 2
	v_add_u32_e32 v137, s78, v86
	ds_read_b128 v[168:171], v137
	s_waitcnt lgkmcnt(9)
	v_lshlrev_b32_e32 v46, 16, v154
	v_and_b32_e32 v47, 0xffff0000, v154
	v_lshlrev_b32_e32 v44, 16, v155
	v_and_b32_e32 v45, 0xffff0000, v155
	s_waitcnt lgkmcnt(8)
	v_pk_fma_f32 v[38:39], v[58:59], v[190:191], v[44:45]
	v_pk_fma_f32 v[36:37], v[56:57], v[188:189], v[46:47]
	ds_read2_b64 v[184:187], v136 offset0:192 offset1:196
	s_waitcnt lgkmcnt(8)
	v_mfma_f32_16x16x32_bf16 v[36:39], v[156:159], v[64:67], v[36:39]
	ds_read2_b64 v[156:159], v136 offset0:200 offset1:204
	s_waitcnt lgkmcnt(8)
	v_mfma_f32_16x16x32_bf16 v[36:39], v[148:151], v[60:63], v[36:39]
	s_waitcnt lgkmcnt(7)
	v_lshlrev_b32_e32 v50, 16, v160
	v_and_b32_e32 v51, 0xffff0000, v160
	v_lshlrev_b32_e32 v48, 16, v161
	v_and_b32_e32 v49, 0xffff0000, v161
	s_waitcnt lgkmcnt(6)
	v_pk_fma_f32 v[44:45], v[52:53], v[176:177], v[50:51]
	v_pk_fma_f32 v[46:47], v[54:55], v[178:179], v[48:49]
	s_waitcnt lgkmcnt(5)
	v_mfma_f32_16x16x32_bf16 v[44:47], v[180:183], v[64:67], v[44:47]
	s_waitcnt lgkmcnt(4)
	v_mfma_f32_16x16x32_bf16 v[44:47], v[140:143], v[60:63], v[44:47]
	s_waitcnt lgkmcnt(3)
	v_lshlrev_b32_e32 v54, 16, v152
	v_and_b32_e32 v55, 0xffff0000, v152
	v_lshlrev_b32_e32 v52, 16, v153
	v_and_b32_e32 v53, 0xffff0000, v153
	s_waitcnt lgkmcnt(2)
	v_pk_fma_f32 v[50:51], v[70:71], v[170:171], v[52:53]
	v_pk_fma_f32 v[48:49], v[68:69], v[168:169], v[54:55]
	s_waitcnt lgkmcnt(1)
	v_mfma_f32_16x16x32_bf16 v[48:51], v[184:187], v[64:67], v[48:51]
	s_waitcnt lgkmcnt(0)
	v_mfma_f32_16x16x32_bf16 v[48:51], v[156:159], v[60:63], v[48:51]
